# FFN-in K-loop: LDS-DMA staging loads issued between the MFMAs of the compute section instead of in the LDS-read section; waits re-derived (vmcnt 6 / 2)
# baseline (speedup 1.0000x reference)
.LBB0_478:
	s_add_u32 s12, s40, 0xfffc0080
	s_addc_u32 s13, s41, -1
	s_add_i32 s85, 0, 0x10000
	s_cmp_eq_u32 s51, 12
	s_cselect_b32 s43, s4, s13
	s_cselect_b32 s42, s9, s12
	v_add_u32_e32 v158, s85, v196
	s_cselect_b32 s13, s17, s50
	s_cselect_b32 s12, s24, s25
	s_add_i32 s27, 0, 0x14000
	ds_read_b128 v[150:153], v158
	ds_read_b128 v[154:157], v158 offset:1024
	ds_read_b128 v[170:173], v158 offset:2048
	ds_read_b128 v[174:177], v158 offset:3072
	v_add_u32_e32 v158, s27, v196
	ds_read_b128 v[178:181], v158
	ds_read_b128 v[182:185], v158 offset:1024
	ds_read_b128 v[186:189], v158 offset:2048
	ds_read_b128 v[200:203], v158 offset:3072
	ds_read_b128 v[204:207], v199
	ds_read_b128 v[208:211], v199 offset:1024
	ds_read_b128 v[212:215], v199 offset:2048
	ds_read_b128 v[234:237], v199 offset:3072
	ds_read_b128 v[238:241], v199 offset:4096
	ds_read_b128 v[242:245], v199 offset:5120
	ds_read_b128 v[246:249], v199 offset:6144
	ds_read_b128 v[222:225], v199 offset:7168
	s_waitcnt vmcnt(6)
	s_waitcnt lgkmcnt(0)
	s_barrier
	s_setprio 1
	s_waitcnt lgkmcnt(0)
	v_mfma_f32_16x16x32_bf16 v[124:127], v[150:153], v[204:207], v[124:127]
	v_mfma_f32_16x16x32_bf16 v[120:123], v[170:173], v[204:207], v[120:123]
	v_mfma_f32_16x16x32_bf16 v[108:111], v[150:153], v[212:215], v[108:111]
	v_lshl_add_u64 v[158:159], s[40:41], 0, v[146:147]
	s_add_i32 m0, s15, 0xc000
	s_nop 0
	global_load_lds_dwordx4 v[158:159], off
	v_mfma_f32_16x16x32_bf16 v[104:107], v[170:173], v[212:215], v[104:107]
	v_mfma_f32_16x16x32_bf16 v[92:95], v[150:153], v[238:241], v[92:95]
	v_mfma_f32_16x16x32_bf16 v[88:91], v[170:173], v[238:241], v[88:91]
	v_mfma_f32_16x16x32_bf16 v[76:79], v[150:153], v[246:249], v[76:79]
	v_mfma_f32_16x16x32_bf16 v[72:75], v[170:173], v[246:249], v[72:75]
	v_mfma_f32_16x16x32_bf16 v[124:127], v[154:157], v[208:211], v[124:127]
	v_lshl_add_u64 v[158:159], s[40:41], 0, v[148:149]
	s_add_i32 m0, s15, 0xe000
	s_nop 0
	global_load_lds_dwordx4 v[158:159], off
	v_mfma_f32_16x16x32_bf16 v[120:123], v[174:177], v[208:211], v[120:123]
	v_mfma_f32_16x16x32_bf16 v[108:111], v[154:157], v[234:237], v[108:111]
	v_mfma_f32_16x16x32_bf16 v[104:107], v[174:177], v[234:237], v[104:107]
	v_mfma_f32_16x16x32_bf16 v[92:95], v[154:157], v[242:245], v[92:95]
	v_mfma_f32_16x16x32_bf16 v[88:91], v[174:177], v[242:245], v[88:91]
	v_mfma_f32_16x16x32_bf16 v[76:79], v[154:157], v[222:225], v[76:79]
	v_mfma_f32_16x16x32_bf16 v[72:75], v[174:177], v[222:225], v[72:75]
	s_setprio 0
	s_setprio 1
	v_mfma_f32_16x16x32_bf16 v[116:119], v[178:181], v[204:207], v[116:119]
	v_mfma_f32_16x16x32_bf16 v[112:115], v[186:189], v[204:207], v[112:115]
	v_mfma_f32_16x16x32_bf16 v[100:103], v[178:181], v[212:215], v[100:103]
	v_mfma_f32_16x16x32_bf16 v[96:99], v[186:189], v[212:215], v[96:99]
	v_mfma_f32_16x16x32_bf16 v[84:87], v[178:181], v[238:241], v[84:87]
	v_mfma_f32_16x16x32_bf16 v[80:83], v[186:189], v[238:241], v[80:83]
	v_mfma_f32_16x16x32_bf16 v[68:71], v[178:181], v[246:249], v[68:71]
	v_mfma_f32_16x16x32_bf16 v[64:67], v[186:189], v[246:249], v[64:67]
	v_mfma_f32_16x16x32_bf16 v[116:119], v[182:185], v[208:211], v[116:119]
	v_mfma_f32_16x16x32_bf16 v[112:115], v[200:203], v[208:211], v[112:115]
	v_mfma_f32_16x16x32_bf16 v[100:103], v[182:185], v[234:237], v[100:103]
	v_mfma_f32_16x16x32_bf16 v[96:99], v[200:203], v[234:237], v[96:99]
	v_mfma_f32_16x16x32_bf16 v[84:87], v[182:185], v[242:245], v[84:87]
	v_mfma_f32_16x16x32_bf16 v[80:83], v[200:203], v[242:245], v[80:83]
	v_mfma_f32_16x16x32_bf16 v[68:71], v[182:185], v[222:225], v[68:71]
	v_mfma_f32_16x16x32_bf16 v[64:67], v[200:203], v[222:225], v[64:67]
	s_setprio 0
	s_barrier
	ds_read_b128 v[204:207], v199 offset:16384
	ds_read_b128 v[208:211], v199 offset:17408
	ds_read_b128 v[212:215], v199 offset:18432
	ds_read_b128 v[222:225], v199 offset:19456
	ds_read_b128 v[234:237], v199 offset:20480
	ds_read_b128 v[238:241], v199 offset:21504
	ds_read_b128 v[242:245], v199 offset:22528
	ds_read_b128 v[246:249], v199 offset:23552
	s_waitcnt vmcnt(2)
	s_waitcnt lgkmcnt(0)
	s_barrier
	s_setprio 1
	s_waitcnt lgkmcnt(0)
	v_mfma_f32_16x16x32_bf16 v[60:63], v[150:153], v[204:207], v[60:63]
	v_mfma_f32_16x16x32_bf16 v[56:59], v[170:173], v[204:207], v[56:59]
	v_mfma_f32_16x16x32_bf16 v[44:47], v[150:153], v[212:215], v[44:47]
	s_add_i32 s85, s85, s86
	v_lshl_add_u64 v[158:159], s[12:13], 0, v[130:131]
	s_mov_b32 m0, s85
	s_nop 0
	global_load_lds_dwordx4 v[158:159], off
	v_mfma_f32_16x16x32_bf16 v[40:43], v[170:173], v[212:215], v[40:43]
	v_mfma_f32_16x16x32_bf16 v[28:31], v[150:153], v[234:237], v[28:31]
	v_mfma_f32_16x16x32_bf16 v[24:27], v[170:173], v[234:237], v[24:27]
	v_mfma_f32_16x16x32_bf16 v[12:15], v[150:153], v[242:245], v[12:15]
	s_add_i32 m0, s85, 0x2000
	s_add_u32 vcc_lo, s12, 0x40000
	v_lshl_add_u64 v[250:251], s[12:13], 0, v[134:135]
	s_addc_u32 vcc_hi, s13, 0
	s_add_i32 s27, s27, s86
	global_load_lds_dwordx4 v[250:251], off
	v_mfma_f32_16x16x32_bf16 v[8:11], v[170:173], v[242:245], v[8:11]
	v_mfma_f32_16x16x32_bf16 v[60:63], v[154:157], v[208:211], v[60:63]
	v_mfma_f32_16x16x32_bf16 v[56:59], v[174:177], v[208:211], v[56:59]
	v_mfma_f32_16x16x32_bf16 v[44:47], v[154:157], v[222:225], v[44:47]
	v_lshl_add_u64 v[226:227], vcc, 0, v[130:131]
	s_mov_b32 m0, s27
	v_lshl_add_u64 v[162:163], s[42:43], 0, v[132:133]
	global_load_lds_dwordx4 v[226:227], off
	v_mfma_f32_16x16x32_bf16 v[40:43], v[174:177], v[222:225], v[40:43]
	v_mfma_f32_16x16x32_bf16 v[28:31], v[154:157], v[238:241], v[28:31]
	v_mfma_f32_16x16x32_bf16 v[24:27], v[174:177], v[238:241], v[24:27]
	v_mfma_f32_16x16x32_bf16 v[12:15], v[154:157], v[246:249], v[12:15]
	v_lshl_add_u64 v[226:227], vcc, 0, v[134:135]
	s_add_i32 m0, s27, 0x2000
	s_nop 0
	global_load_lds_dwordx4 v[226:227], off
	v_mfma_f32_16x16x32_bf16 v[8:11], v[174:177], v[246:249], v[8:11]
	s_setprio 0
	s_setprio 1
	v_mfma_f32_16x16x32_bf16 v[52:55], v[178:181], v[204:207], v[52:55]
	v_mfma_f32_16x16x32_bf16 v[48:51], v[186:189], v[204:207], v[48:51]
	v_mfma_f32_16x16x32_bf16 v[36:39], v[178:181], v[212:215], v[36:39]
	v_lshl_add_u64 v[226:227], s[42:43], 0, v[128:129]
	s_mov_b32 m0, s15
	s_nop 0
	global_load_lds_dwordx4 v[226:227], off
	v_mfma_f32_16x16x32_bf16 v[32:35], v[186:189], v[212:215], v[32:35]
	v_mfma_f32_16x16x32_bf16 v[20:23], v[178:181], v[234:237], v[20:23]
	v_mfma_f32_16x16x32_bf16 v[16:19], v[186:189], v[234:237], v[16:19]
	v_mfma_f32_16x16x32_bf16 v[4:7], v[178:181], v[242:245], v[4:7]
	s_mov_b32 m0, s87
	s_nop 0
	global_load_lds_dwordx4 v[162:163], off
	v_mfma_f32_16x16x32_bf16 v[0:3], v[186:189], v[242:245], v[0:3]
	v_mfma_f32_16x16x32_bf16 v[52:55], v[182:185], v[208:211], v[52:55]
	v_mfma_f32_16x16x32_bf16 v[48:51], v[200:203], v[208:211], v[48:51]
	v_mfma_f32_16x16x32_bf16 v[36:39], v[182:185], v[222:225], v[36:39]
	v_mfma_f32_16x16x32_bf16 v[32:35], v[200:203], v[222:225], v[32:35]
	v_mfma_f32_16x16x32_bf16 v[20:23], v[182:185], v[238:241], v[20:23]
	v_mfma_f32_16x16x32_bf16 v[16:19], v[200:203], v[238:241], v[16:19]
	v_mfma_f32_16x16x32_bf16 v[4:7], v[182:185], v[246:249], v[4:7]
	v_mfma_f32_16x16x32_bf16 v[0:3], v[200:203], v[246:249], v[0:3]
	s_setprio 0
	s_barrier
	s_add_i32 s27, 0, 0x18000
	v_add_u32_e32 v160, s27, v196
	s_add_i32 s85, 0, 0x1c000
	ds_read_b128 v[150:153], v160
	ds_read_b128 v[154:157], v160 offset:1024
	ds_read_b128 v[170:173], v160 offset:2048
	ds_read_b128 v[174:177], v160 offset:3072
	v_add_u32_e32 v160, s85, v196
	ds_read_b128 v[178:181], v160
	ds_read_b128 v[182:185], v160 offset:1024
	ds_read_b128 v[186:189], v160 offset:2048
	ds_read_b128 v[200:203], v160 offset:3072
	ds_read_b128 v[204:207], v199 offset:32768
	ds_read_b128 v[208:211], v199 offset:33792
	ds_read_b128 v[212:215], v199 offset:34816
	ds_read_b128 v[222:225], v199 offset:35840
	ds_read_b128 v[234:237], v199 offset:36864
	ds_read_b128 v[238:241], v199 offset:37888
	ds_read_b128 v[242:245], v199 offset:38912
	ds_read_b128 v[246:249], v199 offset:39936
	s_waitcnt vmcnt(6)
	s_waitcnt lgkmcnt(0)
	s_barrier
	s_setprio 1
	s_waitcnt lgkmcnt(0)
	v_mfma_f32_16x16x32_bf16 v[124:127], v[150:153], v[204:207], v[124:127]
	v_mfma_f32_16x16x32_bf16 v[120:123], v[170:173], v[204:207], v[120:123]
	v_mfma_f32_16x16x32_bf16 v[108:111], v[150:153], v[212:215], v[108:111]
	s_add_u32 s42, s42, 0x40000
	s_addc_u32 s43, s43, 0
	s_mov_b32 m0, s88
	v_lshl_add_u64 v[164:165], s[42:43], 0, v[128:129]
	global_load_lds_dwordx4 v[164:165], off
	v_mfma_f32_16x16x32_bf16 v[104:107], v[170:173], v[212:215], v[104:107]
	v_mfma_f32_16x16x32_bf16 v[92:95], v[150:153], v[234:237], v[92:95]
	v_mfma_f32_16x16x32_bf16 v[88:91], v[170:173], v[234:237], v[88:91]
	v_mfma_f32_16x16x32_bf16 v[76:79], v[150:153], v[242:245], v[76:79]
	v_mfma_f32_16x16x32_bf16 v[72:75], v[170:173], v[242:245], v[72:75]
	v_mfma_f32_16x16x32_bf16 v[124:127], v[154:157], v[208:211], v[124:127]
	v_lshl_add_u64 v[164:165], s[42:43], 0, v[132:133]
	s_mov_b32 m0, s89
	s_nop 0
	global_load_lds_dwordx4 v[164:165], off
	v_mfma_f32_16x16x32_bf16 v[120:123], v[174:177], v[208:211], v[120:123]
	v_mfma_f32_16x16x32_bf16 v[108:111], v[154:157], v[222:225], v[108:111]
	v_mfma_f32_16x16x32_bf16 v[104:107], v[174:177], v[222:225], v[104:107]
	v_mfma_f32_16x16x32_bf16 v[92:95], v[154:157], v[238:241], v[92:95]
	v_mfma_f32_16x16x32_bf16 v[88:91], v[174:177], v[238:241], v[88:91]
	v_mfma_f32_16x16x32_bf16 v[76:79], v[154:157], v[246:249], v[76:79]
	v_mfma_f32_16x16x32_bf16 v[72:75], v[174:177], v[246:249], v[72:75]
	s_setprio 0
	s_setprio 1
	v_mfma_f32_16x16x32_bf16 v[116:119], v[178:181], v[204:207], v[116:119]
	v_mfma_f32_16x16x32_bf16 v[112:115], v[186:189], v[204:207], v[112:115]
	v_mfma_f32_16x16x32_bf16 v[100:103], v[178:181], v[212:215], v[100:103]
	v_mfma_f32_16x16x32_bf16 v[96:99], v[186:189], v[212:215], v[96:99]
	v_mfma_f32_16x16x32_bf16 v[84:87], v[178:181], v[234:237], v[84:87]
	v_mfma_f32_16x16x32_bf16 v[80:83], v[186:189], v[234:237], v[80:83]
	v_mfma_f32_16x16x32_bf16 v[68:71], v[178:181], v[242:245], v[68:71]
	v_mfma_f32_16x16x32_bf16 v[64:67], v[186:189], v[242:245], v[64:67]
	v_mfma_f32_16x16x32_bf16 v[116:119], v[182:185], v[208:211], v[116:119]
	v_mfma_f32_16x16x32_bf16 v[112:115], v[200:203], v[208:211], v[112:115]
	v_mfma_f32_16x16x32_bf16 v[100:103], v[182:185], v[222:225], v[100:103]
	v_mfma_f32_16x16x32_bf16 v[96:99], v[200:203], v[222:225], v[96:99]
	v_mfma_f32_16x16x32_bf16 v[84:87], v[182:185], v[238:241], v[84:87]
	v_mfma_f32_16x16x32_bf16 v[80:83], v[200:203], v[238:241], v[80:83]
	v_mfma_f32_16x16x32_bf16 v[68:71], v[182:185], v[246:249], v[68:71]
	v_mfma_f32_16x16x32_bf16 v[64:67], v[200:203], v[246:249], v[64:67]
	s_setprio 0
	s_barrier
	ds_read_b128 v[204:207], v199 offset:49152
	ds_read_b128 v[208:211], v199 offset:50176
	ds_read_b128 v[212:215], v199 offset:51200
	ds_read_b128 v[222:225], v199 offset:52224
	ds_read_b128 v[234:237], v199 offset:53248
	ds_read_b128 v[238:241], v199 offset:54272
	ds_read_b128 v[242:245], v199 offset:55296
	ds_read_b128 v[246:249], v199 offset:56320
	s_waitcnt vmcnt(2)
	s_waitcnt lgkmcnt(0)
	s_barrier
	s_setprio 1
	s_waitcnt lgkmcnt(0)
	v_mfma_f32_16x16x32_bf16 v[60:63], v[150:153], v[204:207], v[60:63]
	v_mfma_f32_16x16x32_bf16 v[56:59], v[170:173], v[204:207], v[56:59]
	v_mfma_f32_16x16x32_bf16 v[44:47], v[150:153], v[212:215], v[44:47]
	s_add_i32 s27, s27, s86
	v_lshl_add_u64 v[158:159], v[158:159], 0, s[48:49]
	s_mov_b32 m0, s27
	s_nop 0
	global_load_lds_dwordx4 v[158:159], off
	v_mfma_f32_16x16x32_bf16 v[40:43], v[170:173], v[212:215], v[40:43]
	v_mfma_f32_16x16x32_bf16 v[28:31], v[150:153], v[234:237], v[28:31]
	v_mfma_f32_16x16x32_bf16 v[24:27], v[170:173], v[234:237], v[24:27]
	v_mfma_f32_16x16x32_bf16 v[12:15], v[150:153], v[242:245], v[12:15]
	s_add_i32 m0, s27, 0x2000
	s_add_u32 s12, s12, 0x40080
	v_lshl_add_u64 v[158:159], v[250:251], 0, s[48:49]
	s_addc_u32 s13, s13, 0
	s_add_i32 s27, s85, s86
	global_load_lds_dwordx4 v[158:159], off
	v_mfma_f32_16x16x32_bf16 v[8:11], v[170:173], v[242:245], v[8:11]
	v_mfma_f32_16x16x32_bf16 v[60:63], v[154:157], v[208:211], v[60:63]
	v_mfma_f32_16x16x32_bf16 v[56:59], v[174:177], v[208:211], v[56:59]
	v_mfma_f32_16x16x32_bf16 v[44:47], v[154:157], v[222:225], v[44:47]
	v_lshl_add_u64 v[158:159], s[12:13], 0, v[130:131]
	s_mov_b32 m0, s27
	s_nop 0
	global_load_lds_dwordx4 v[158:159], off
	v_mfma_f32_16x16x32_bf16 v[40:43], v[174:177], v[222:225], v[40:43]
	v_mfma_f32_16x16x32_bf16 v[28:31], v[154:157], v[238:241], v[28:31]
	v_mfma_f32_16x16x32_bf16 v[24:27], v[174:177], v[238:241], v[24:27]
	v_mfma_f32_16x16x32_bf16 v[12:15], v[154:157], v[246:249], v[12:15]
	v_lshl_add_u64 v[158:159], s[12:13], 0, v[134:135]
	s_add_i32 m0, s27, 0x2000
	s_nop 0
	global_load_lds_dwordx4 v[158:159], off
	v_mfma_f32_16x16x32_bf16 v[8:11], v[174:177], v[246:249], v[8:11]
	s_setprio 0
	s_setprio 1
	v_mfma_f32_16x16x32_bf16 v[52:55], v[178:181], v[204:207], v[52:55]
	v_mfma_f32_16x16x32_bf16 v[48:51], v[186:189], v[204:207], v[48:51]
	v_mfma_f32_16x16x32_bf16 v[36:39], v[178:181], v[212:215], v[36:39]
	v_lshl_add_u64 v[158:159], v[226:227], 0, s[48:49]
	s_mov_b32 m0, s92
	s_nop 0
	global_load_lds_dwordx4 v[158:159], off
	v_mfma_f32_16x16x32_bf16 v[32:35], v[186:189], v[212:215], v[32:35]
	v_mfma_f32_16x16x32_bf16 v[20:23], v[178:181], v[234:237], v[20:23]
	v_mfma_f32_16x16x32_bf16 v[16:19], v[186:189], v[234:237], v[16:19]
	v_mfma_f32_16x16x32_bf16 v[4:7], v[178:181], v[242:245], v[4:7]
	v_lshl_add_u64 v[158:159], v[162:163], 0, s[48:49]
	s_mov_b32 m0, s93
	s_nop 0
	global_load_lds_dwordx4 v[158:159], off
	v_mfma_f32_16x16x32_bf16 v[0:3], v[186:189], v[242:245], v[0:3]
	v_mfma_f32_16x16x32_bf16 v[52:55], v[182:185], v[208:211], v[52:55]
	v_mfma_f32_16x16x32_bf16 v[48:51], v[200:203], v[208:211], v[48:51]
	v_mfma_f32_16x16x32_bf16 v[36:39], v[182:185], v[222:225], v[36:39]
	v_mfma_f32_16x16x32_bf16 v[32:35], v[200:203], v[222:225], v[32:35]
	v_mfma_f32_16x16x32_bf16 v[20:23], v[182:185], v[238:241], v[20:23]
	v_mfma_f32_16x16x32_bf16 v[16:19], v[200:203], v[238:241], v[16:19]
	v_mfma_f32_16x16x32_bf16 v[4:7], v[182:185], v[246:249], v[4:7]
	v_mfma_f32_16x16x32_bf16 v[0:3], v[200:203], v[246:249], v[0:3]
	s_setprio 0
	s_barrier
	s_add_i32 s51, s51, 2
	s_add_u32 s40, s40, 0x100
	s_addc_u32 s41, s41, 0
	s_add_u32 s25, s25, 0x100
	s_addc_u32 s50, s50, 0
	s_cmp_gt_u32 s51, 13
	s_cbranch_scc0 .LBB0_478
	s_and_b64 vcc, exec, s[10:11]
	s_cbranch_vccz .LBB0_481
	s_barrier
